# LoRA-input phase rewritten by hand (all row loads of a wave in flight, branch-free activations)
# speedup vs baseline: 1.0113x; 1.0082x over previous
; __device__ __forceinline__ int fresh_tid(int wv) { int l; asm volatile("v_mbcnt_lo_u32_b32 %0, -1, 0\n\tv_mbcnt_hi_u32_b32 %0, -1, %0" : "=v"(l)); return wv * 64 + l; }
; __device__ __forceinline__ unsigned cvt_pk_bf16(float lo, float hi) { const f32x2_t v = {lo, hi}; const bf16x2_t b = __builtin_convertvector(v, bf16x2_t); return __builtin_bit_cast(unsigned, b); }
; __device__ __forceinline__ float lo_bf(unsigned x) { return __uint_as_float(x << 16); }
; __device__ __forceinline__ float hi_bf(unsigned x) { return __uint_as_float(x & 0xffff0000u); }
; __device__ __forceinline__ float sigmoid_f(float x) { return __builtin_amdgcn_rcpf(1.0f + __expf(-x)); }
; __device__ __forceinline__ void lora_prep(PR P, const int wv) {
;     const int tid = fresh_tid(wv); const int lane = tid & 63; const int gw = blockIdx.x * 8 + (tid >> 6), nw = gridDim.x * 8;
;     const bf16_t* PS = (const bf16_t*)(P.ws + WS_BIG); bf16_t* LA = (bf16_t*)(P.ws + WS_LA);
;     const float4 mu = *(const float4*)(P.mu + 1536 + lane * 4); const int kind = lane >> 4;
;     if (gw >= MT) return;
;     const int last = gw + ((MT - 1 - gw) / nw) * nw;
;     u32x2 c, p, nc, np;
;     { const int pr = prev_row(gw); c = *(const u32x2*)(PS + (size_t)gw * NCOLS + 1536 + lane * 4); p = *(const u32x2*)(PS + (size_t)(pr >= 0 ? pr : gw) * NCOLS + 1536 + lane * 4); }
;     for (int row = gw; row < MT; row += nw) {
;         const int nrow = row + nw < MT ? row + nw : last; const int npr = prev_row(nrow);
;         nc = *(const u32x2*)(PS + (size_t)nrow * NCOLS + 1536 + lane * 4); np = *(const u32x2*)(PS + (size_t)(npr >= 0 ? npr : nrow) * NCOLS + 1536 + lane * 4);
;         if (prev_row(row) < 0) p = (u32x2){0u, 0u};
;         float v[4]; const float cu[4] = {lo_bf(c.x), hi_bf(c.x), lo_bf(c.y), hi_bf(c.y)}, pv[4] = {lo_bf(p.x), hi_bf(p.x), lo_bf(p.y), hi_bf(p.y)}, m4[4] = {mu.x, mu.y, mu.z, mu.w};
; #pragma unroll
;         for (int j = 0; j < 4; ++j) { float x = cu[j] + (pv[j] - cu[j]) * m4[j];
;             if (kind == 0) x = 1.0f - 2.0f * __builtin_amdgcn_rcpf(__expf(2.0f * x) + 1.0f); else if (kind >= 2) x = sigmoid_f(x);
;             v[j] = x; }
;         u32x2 w; w.x = pg8::cvt_pk_bf16(v[0], v[1]); w.y = pg8::cvt_pk_bf16(v[2], v[3]);
;         *(u32x2*)(LA + (size_t)row * 256 + lane * 4) = w;
.LBB0_431:
	s_or_b64 exec, exec, s[8:9]
	s_waitcnt lgkmcnt(0)
	s_barrier
	s_load_dwordx2 s[16:17], s[0:1], 0xd8
	v_mbcnt_lo_u32_b32 v0, -1, 0
	v_mbcnt_hi_u32_b32 v0, -1, v0
	s_movk_i32 s4, 0x4200
	v_add_u32_e32 v9, s33, v0
	v_ashrrev_i32_e32 v1, 6, v9
	v_add_u32_e32 v10, s73, v1
	v_cmp_gt_i32_e32 vcc, s4, v10
	s_and_saveexec_b64 s[4:5], vcc
	s_xor_b64 s[18:19], exec, s[4:5]
	s_cbranch_execz .LBB0_463
	s_load_dwordx2 s[4:5], s[0:1], 0x50
	v_lshlrev_b32_e32 v1, 4, v0
	v_lshlrev_b32_e32 v2, 3, v0
	v_lshrrev_b32_e32 v3, 4, v0
	v_cmp_eq_u32_e64 s[22:23], 0, v3
	v_cmp_eq_u32_e64 s[24:25], 1, v3
	v_mov_b32_e32 v3, 0xbfb8aa3b
	v_mov_b32_e32 v8, 0x4038aa3b
	s_lshr_b32 s6, s33, 6
	s_add_i32 s6, s6, s73
	s_cmp_eq_u32 s6, 0
	s_cselect_b32 s49, 0, 0x1e00
	v_cndmask_b32_e64 v3, v3, v8, s[22:23]
	s_waitcnt lgkmcnt(0)
	s_add_u32 s4, s4, 0x1800
	s_addc_u32 s5, s5, 0
	global_load_dwordx4 v[4:7], v1, s[4:5]
	s_add_u32 s8, s16, 0x3d45400
	s_addc_u32 s9, s17, 0
	s_add_u32 s10, s16, 0xcb64800
	s_addc_u32 s11, s17, 0
	s_mul_i32 s7, s6, 0x1e00
	s_add_u32 s12, s8, s7
	s_addc_u32 s13, s9, 0
	s_sub_u32 s14, s12, s49
	s_subb_u32 s15, s13, 0
	global_load_dwordx2 v[32:33], v2, s[12:13]
	global_load_dwordx2 v[34:35], v2, s[14:15]
	s_add_u32 s12, s12, 0xf00000
	s_addc_u32 s13, s13, 0
	s_sub_u32 s14, s12, s49
	s_subb_u32 s15, s13, 0
	global_load_dwordx2 v[36:37], v2, s[12:13]
	global_load_dwordx2 v[38:39], v2, s[14:15]
	s_add_u32 s12, s12, 0xf00000
	s_addc_u32 s13, s13, 0
	s_sub_u32 s14, s12, s49
	s_subb_u32 s15, s13, 0
	global_load_dwordx2 v[40:41], v2, s[12:13]
	global_load_dwordx2 v[42:43], v2, s[14:15]
	s_add_u32 s12, s12, 0xf00000
	s_addc_u32 s13, s13, 0
	s_sub_u32 s14, s12, s49
	s_subb_u32 s15, s13, 0
	global_load_dwordx2 v[44:45], v2, s[12:13]
	global_load_dwordx2 v[46:47], v2, s[14:15]
	s_add_u32 s12, s12, 0xf00000
	s_addc_u32 s13, s13, 0
	s_sub_u32 s14, s12, s49
	s_subb_u32 s15, s13, 0
	global_load_dwordx2 v[48:49], v2, s[12:13]
	global_load_dwordx2 v[50:51], v2, s[14:15]
	s_add_u32 s12, s12, 0xf00000
	s_addc_u32 s13, s13, 0
	s_sub_u32 s14, s12, s49
	s_subb_u32 s15, s13, 0
	global_load_dwordx2 v[52:53], v2, s[12:13]
	global_load_dwordx2 v[54:55], v2, s[14:15]
	s_add_u32 s12, s12, 0xf00000
	s_addc_u32 s13, s13, 0
	s_sub_u32 s14, s12, s49
	s_subb_u32 s15, s13, 0
	global_load_dwordx2 v[56:57], v2, s[12:13]
	global_load_dwordx2 v[58:59], v2, s[14:15]
	s_add_u32 s12, s12, 0xf00000
	s_addc_u32 s13, s13, 0
	s_sub_u32 s14, s12, s49
	s_subb_u32 s15, s13, 0
	global_load_dwordx2 v[60:61], v2, s[12:13]
	global_load_dwordx2 v[62:63], v2, s[14:15]
	s_cmp_lt_u32 s6, 0x200
	s_cbranch_scc0 .Lp5_no9a
	s_add_u32 s12, s12, 0xf00000
	s_addc_u32 s13, s13, 0
	s_and_b32 s7, s6, 3
	s_cmp_eq_u32 s7, 0
	s_cbranch_scc1 .Lp5_first
	s_sub_u32 s14, s12, 0x1e00
	s_subb_u32 s15, s13, 0
	s_branch .Lp5_ld9
.Lp5_first:
	s_lshr_b32 s7, s6, 2
	s_addk_i32 s7, 0x4200
	s_mul_i32 s7, s7, 0x1e00
	s_add_u32 s14, s8, s7
	s_addc_u32 s15, s9, 0
.Lp5_ld9:
	global_load_dwordx2 v[64:65], v2, s[12:13]
	global_load_dwordx2 v[66:67], v2, s[14:15]
.Lp5_no9a:
	s_waitcnt vmcnt(14)
	v_lshlrev_b32_e32 v8, 16, v32
	v_and_b32_e32 v9, 0xffff0000, v32
	v_lshlrev_b32_e32 v10, 16, v33
	v_and_b32_e32 v11, 0xffff0000, v33
	v_lshlrev_b32_e32 v12, 16, v34
	v_and_b32_e32 v13, 0xffff0000, v34
	v_lshlrev_b32_e32 v14, 16, v35
	v_and_b32_e32 v15, 0xffff0000, v35
	s_cmp_lg_u32 s6, 0
	s_cbranch_scc1 .Lp5_keep0
	v_mov_b32_e32 v12, 0
	v_mov_b32_e32 v13, 0
	v_mov_b32_e32 v14, 0
	v_mov_b32_e32 v15, 0
.Lp5_keep0:
	v_pk_add_f32 v[12:13], v[12:13], v[8:9] neg_lo:[0,1] neg_hi:[0,1]
	v_pk_add_f32 v[14:15], v[14:15], v[10:11] neg_lo:[0,1] neg_hi:[0,1]
	v_pk_fma_f32 v[16:17], v[12:13], v[4:5], v[8:9]
	v_pk_fma_f32 v[18:19], v[14:15], v[6:7], v[10:11]
	v_mul_f32_e32 v20, v3, v16
	v_mul_f32_e32 v21, v3, v17
	v_mul_f32_e32 v22, v3, v18
	v_mul_f32_e32 v23, v3, v19
	v_exp_f32_e32 v20, v20
	v_exp_f32_e32 v21, v21
	v_exp_f32_e32 v22, v22
	v_exp_f32_e32 v23, v23
	v_add_f32_e32 v20, 1.0, v20
	v_add_f32_e32 v21, 1.0, v21
	v_add_f32_e32 v22, 1.0, v22
	v_add_f32_e32 v23, 1.0, v23
	v_rcp_f32_e32 v20, v20
	v_rcp_f32_e32 v21, v21
	v_rcp_f32_e32 v22, v22
	v_rcp_f32_e32 v23, v23
	v_fma_f32 v24, v20, -2.0, 1.0
	v_fma_f32 v25, v21, -2.0, 1.0
	v_fma_f32 v26, v22, -2.0, 1.0
	v_fma_f32 v27, v23, -2.0, 1.0
	v_cndmask_b32_e64 v20, v20, v16, s[24:25]
	v_cndmask_b32_e64 v21, v21, v17, s[24:25]
	v_cndmask_b32_e64 v22, v22, v18, s[24:25]
	v_cndmask_b32_e64 v23, v23, v19, s[24:25]
	v_cndmask_b32_e64 v20, v20, v24, s[22:23]
	v_cndmask_b32_e64 v21, v21, v25, s[22:23]
	v_cndmask_b32_e64 v22, v22, v26, s[22:23]
	v_cndmask_b32_e64 v23, v23, v27, s[22:23]
	v_cvt_pk_bf16_f32 v20, v20, v21
	v_cvt_pk_bf16_f32 v21, v22, v23
	s_lshl_b32 s7, s6, 9
	s_add_u32 s20, s10, s7
	s_addc_u32 s21, s11, 0
	global_store_dwordx2 v2, v[20:21], s[20:21]
	s_waitcnt vmcnt(13)
	v_lshlrev_b32_e32 v8, 16, v36
	v_and_b32_e32 v9, 0xffff0000, v36
	v_lshlrev_b32_e32 v10, 16, v37
	v_and_b32_e32 v11, 0xffff0000, v37
	v_lshlrev_b32_e32 v12, 16, v38
	v_and_b32_e32 v13, 0xffff0000, v38
	v_lshlrev_b32_e32 v14, 16, v39
	v_and_b32_e32 v15, 0xffff0000, v39
	s_cmp_lg_u32 s6, 0
	s_cbranch_scc1 .Lp5_keep1
	v_mov_b32_e32 v12, 0
	v_mov_b32_e32 v13, 0
	v_mov_b32_e32 v14, 0
	v_mov_b32_e32 v15, 0
; __device__ __forceinline__ unsigned cvt_pk_bf16(float lo, float hi) { const f32x2_t v = {lo, hi}; const bf16x2_t b = __builtin_convertvector(v, bf16x2_t); return __builtin_bit_cast(unsigned, b); }
; __device__ __forceinline__ float lo_bf(unsigned x) { return __uint_as_float(x << 16); }
; __device__ __forceinline__ float hi_bf(unsigned x) { return __uint_as_float(x & 0xffff0000u); }
; __device__ __forceinline__ float sigmoid_f(float x) { return __builtin_amdgcn_rcpf(1.0f + __expf(-x)); }
; __device__ __forceinline__ void lora_prep(PR P, const int wv) {
;     ...
;     for (int row = gw; row < MT; row += nw) {
;         const int nrow = row + nw < MT ? row + nw : last; const int npr = prev_row(nrow);
;         nc = *(const u32x2*)(PS + (size_t)nrow * NCOLS + 1536 + lane * 4); np = *(const u32x2*)(PS + (size_t)(npr >= 0 ? npr : nrow) * NCOLS + 1536 + lane * 4);
;         if (prev_row(row) < 0) p = (u32x2){0u, 0u};
;         float v[4]; const float cu[4] = {lo_bf(c.x), hi_bf(c.x), lo_bf(c.y), hi_bf(c.y)}, pv[4] = {lo_bf(p.x), hi_bf(p.x), lo_bf(p.y), hi_bf(p.y)}, m4[4] = {mu.x, mu.y, mu.z, mu.w};
; #pragma unroll
;         for (int j = 0; j < 4; ++j) { float x = cu[j] + (pv[j] - cu[j]) * m4[j];
;             if (kind == 0) x = 1.0f - 2.0f * __builtin_amdgcn_rcpf(__expf(2.0f * x) + 1.0f); else if (kind >= 2) x = sigmoid_f(x);
;             v[j] = x; }
;         u32x2 w; w.x = pg8::cvt_pk_bf16(v[0], v[1]); w.y = pg8::cvt_pk_bf16(v[2], v[3]);
;         *(u32x2*)(LA + (size_t)row * 256 + lane * 4) = w;
;         c = nc; p = np;
.Lp5_keep1:
	v_pk_add_f32 v[12:13], v[12:13], v[8:9] neg_lo:[0,1] neg_hi:[0,1]
	v_pk_add_f32 v[14:15], v[14:15], v[10:11] neg_lo:[0,1] neg_hi:[0,1]
	v_pk_fma_f32 v[16:17], v[12:13], v[4:5], v[8:9]
	v_pk_fma_f32 v[18:19], v[14:15], v[6:7], v[10:11]
	v_mul_f32_e32 v20, v3, v16
	v_mul_f32_e32 v21, v3, v17
	v_mul_f32_e32 v22, v3, v18
	v_mul_f32_e32 v23, v3, v19
	v_exp_f32_e32 v20, v20
	v_exp_f32_e32 v21, v21
	v_exp_f32_e32 v22, v22
	v_exp_f32_e32 v23, v23
	v_add_f32_e32 v20, 1.0, v20
	v_add_f32_e32 v21, 1.0, v21
	v_add_f32_e32 v22, 1.0, v22
	v_add_f32_e32 v23, 1.0, v23
	v_rcp_f32_e32 v20, v20
	v_rcp_f32_e32 v21, v21
	v_rcp_f32_e32 v22, v22
	v_rcp_f32_e32 v23, v23
	v_fma_f32 v24, v20, -2.0, 1.0
	v_fma_f32 v25, v21, -2.0, 1.0
	v_fma_f32 v26, v22, -2.0, 1.0
	v_fma_f32 v27, v23, -2.0, 1.0
	v_cndmask_b32_e64 v20, v20, v16, s[24:25]
	v_cndmask_b32_e64 v21, v21, v17, s[24:25]
	v_cndmask_b32_e64 v22, v22, v18, s[24:25]
	v_cndmask_b32_e64 v23, v23, v19, s[24:25]
	v_cndmask_b32_e64 v20, v20, v24, s[22:23]
	v_cndmask_b32_e64 v21, v21, v25, s[22:23]
	v_cndmask_b32_e64 v22, v22, v26, s[22:23]
	v_cndmask_b32_e64 v23, v23, v27, s[22:23]
	v_cvt_pk_bf16_f32 v20, v20, v21
	v_cvt_pk_bf16_f32 v21, v22, v23
	s_add_u32 s20, s20, 0x100000
	s_addc_u32 s21, s21, 0
	global_store_dwordx2 v2, v[20:21], s[20:21]
	s_waitcnt vmcnt(12)
	v_lshlrev_b32_e32 v8, 16, v40
	v_and_b32_e32 v9, 0xffff0000, v40
	v_lshlrev_b32_e32 v10, 16, v41
	v_and_b32_e32 v11, 0xffff0000, v41
	v_lshlrev_b32_e32 v12, 16, v42
	v_and_b32_e32 v13, 0xffff0000, v42
	v_lshlrev_b32_e32 v14, 16, v43
	v_and_b32_e32 v15, 0xffff0000, v43
	s_cmp_lg_u32 s6, 0
	s_cbranch_scc1 .Lp5_keep2
	v_mov_b32_e32 v12, 0
	v_mov_b32_e32 v13, 0
	v_mov_b32_e32 v14, 0
	v_mov_b32_e32 v15, 0
.Lp5_keep2:
	v_pk_add_f32 v[12:13], v[12:13], v[8:9] neg_lo:[0,1] neg_hi:[0,1]
	v_pk_add_f32 v[14:15], v[14:15], v[10:11] neg_lo:[0,1] neg_hi:[0,1]
	v_pk_fma_f32 v[16:17], v[12:13], v[4:5], v[8:9]
	v_pk_fma_f32 v[18:19], v[14:15], v[6:7], v[10:11]
	v_mul_f32_e32 v20, v3, v16
	v_mul_f32_e32 v21, v3, v17
	v_mul_f32_e32 v22, v3, v18
	v_mul_f32_e32 v23, v3, v19
	v_exp_f32_e32 v20, v20
	v_exp_f32_e32 v21, v21
	v_exp_f32_e32 v22, v22
	v_exp_f32_e32 v23, v23
	v_add_f32_e32 v20, 1.0, v20
	v_add_f32_e32 v21, 1.0, v21
	v_add_f32_e32 v22, 1.0, v22
	v_add_f32_e32 v23, 1.0, v23
	v_rcp_f32_e32 v20, v20
	v_rcp_f32_e32 v21, v21
	v_rcp_f32_e32 v22, v22
	v_rcp_f32_e32 v23, v23
	v_fma_f32 v24, v20, -2.0, 1.0
	v_fma_f32 v25, v21, -2.0, 1.0
	v_fma_f32 v26, v22, -2.0, 1.0
	v_fma_f32 v27, v23, -2.0, 1.0
	v_cndmask_b32_e64 v20, v20, v16, s[24:25]
	v_cndmask_b32_e64 v21, v21, v17, s[24:25]
	v_cndmask_b32_e64 v22, v22, v18, s[24:25]
	v_cndmask_b32_e64 v23, v23, v19, s[24:25]
	v_cndmask_b32_e64 v20, v20, v24, s[22:23]
	v_cndmask_b32_e64 v21, v21, v25, s[22:23]
	v_cndmask_b32_e64 v22, v22, v26, s[22:23]
	v_cndmask_b32_e64 v23, v23, v27, s[22:23]
	v_cvt_pk_bf16_f32 v20, v20, v21
	v_cvt_pk_bf16_f32 v21, v22, v23
	s_add_u32 s20, s20, 0x100000
	s_addc_u32 s21, s21, 0
	global_store_dwordx2 v2, v[20:21], s[20:21]
	s_waitcnt vmcnt(11)
	v_lshlrev_b32_e32 v8, 16, v44
	v_and_b32_e32 v9, 0xffff0000, v44
	v_lshlrev_b32_e32 v10, 16, v45
	v_and_b32_e32 v11, 0xffff0000, v45
	v_lshlrev_b32_e32 v12, 16, v46
	v_and_b32_e32 v13, 0xffff0000, v46
	v_lshlrev_b32_e32 v14, 16, v47
	v_and_b32_e32 v15, 0xffff0000, v47
	s_cmp_lg_u32 s6, 0
	s_cbranch_scc1 .Lp5_keep3
	v_mov_b32_e32 v12, 0
	v_mov_b32_e32 v13, 0
	v_mov_b32_e32 v14, 0
	v_mov_b32_e32 v15, 0
.Lp5_keep3:
	v_pk_add_f32 v[12:13], v[12:13], v[8:9] neg_lo:[0,1] neg_hi:[0,1]
	v_pk_add_f32 v[14:15], v[14:15], v[10:11] neg_lo:[0,1] neg_hi:[0,1]
	v_pk_fma_f32 v[16:17], v[12:13], v[4:5], v[8:9]
	v_pk_fma_f32 v[18:19], v[14:15], v[6:7], v[10:11]
	v_mul_f32_e32 v20, v3, v16
	v_mul_f32_e32 v21, v3, v17
	v_mul_f32_e32 v22, v3, v18
	v_mul_f32_e32 v23, v3, v19
	v_exp_f32_e32 v20, v20
	v_exp_f32_e32 v21, v21
	v_exp_f32_e32 v22, v22
	v_exp_f32_e32 v23, v23
	v_add_f32_e32 v20, 1.0, v20
	v_add_f32_e32 v21, 1.0, v21
	v_add_f32_e32 v22, 1.0, v22
	v_add_f32_e32 v23, 1.0, v23
	v_rcp_f32_e32 v20, v20
	v_rcp_f32_e32 v21, v21
	v_rcp_f32_e32 v22, v22
	v_rcp_f32_e32 v23, v23
	v_fma_f32 v24, v20, -2.0, 1.0
	v_fma_f32 v25, v21, -2.0, 1.0
	v_fma_f32 v26, v22, -2.0, 1.0
	v_fma_f32 v27, v23, -2.0, 1.0
	v_cndmask_b32_e64 v20, v20, v16, s[24:25]
	v_cndmask_b32_e64 v21, v21, v17, s[24:25]
	v_cndmask_b32_e64 v22, v22, v18, s[24:25]
	v_cndmask_b32_e64 v23, v23, v19, s[24:25]
	v_cndmask_b32_e64 v20, v20, v24, s[22:23]
	v_cndmask_b32_e64 v21, v21, v25, s[22:23]
	v_cndmask_b32_e64 v22, v22, v26, s[22:23]
	v_cndmask_b32_e64 v23, v23, v27, s[22:23]
	v_cvt_pk_bf16_f32 v20, v20, v21
	v_cvt_pk_bf16_f32 v21, v22, v23
	s_add_u32 s20, s20, 0x100000
	s_addc_u32 s21, s21, 0
	global_store_dwordx2 v2, v[20:21], s[20:21]
	s_waitcnt vmcnt(10)
	v_lshlrev_b32_e32 v8, 16, v48
	v_and_b32_e32 v9, 0xffff0000, v48
	v_lshlrev_b32_e32 v10, 16, v49
	v_and_b32_e32 v11, 0xffff0000, v49
	v_lshlrev_b32_e32 v12, 16, v50
	v_and_b32_e32 v13, 0xffff0000, v50
	v_lshlrev_b32_e32 v14, 16, v51
	v_and_b32_e32 v15, 0xffff0000, v51
	s_cmp_lg_u32 s6, 0
	s_cbranch_scc1 .Lp5_keep4
	v_mov_b32_e32 v12, 0
	v_mov_b32_e32 v13, 0
	v_mov_b32_e32 v14, 0
	v_mov_b32_e32 v15, 0
; __device__ __forceinline__ unsigned cvt_pk_bf16(float lo, float hi) { const f32x2_t v = {lo, hi}; const bf16x2_t b = __builtin_convertvector(v, bf16x2_t); return __builtin_bit_cast(unsigned, b); }
; __device__ __forceinline__ float lo_bf(unsigned x) { return __uint_as_float(x << 16); }
; __device__ __forceinline__ float hi_bf(unsigned x) { return __uint_as_float(x & 0xffff0000u); }
; __device__ __forceinline__ float sigmoid_f(float x) { return __builtin_amdgcn_rcpf(1.0f + __expf(-x)); }
; __device__ __forceinline__ void lora_prep(PR P, const int wv) {
;     ...
;     for (int row = gw; row < MT; row += nw) {
;         const int nrow = row + nw < MT ? row + nw : last; const int npr = prev_row(nrow);
;         nc = *(const u32x2*)(PS + (size_t)nrow * NCOLS + 1536 + lane * 4); np = *(const u32x2*)(PS + (size_t)(npr >= 0 ? npr : nrow) * NCOLS + 1536 + lane * 4);
;         if (prev_row(row) < 0) p = (u32x2){0u, 0u};
;         float v[4]; const float cu[4] = {lo_bf(c.x), hi_bf(c.x), lo_bf(c.y), hi_bf(c.y)}, pv[4] = {lo_bf(p.x), hi_bf(p.x), lo_bf(p.y), hi_bf(p.y)}, m4[4] = {mu.x, mu.y, mu.z, mu.w};
; #pragma unroll
;         for (int j = 0; j < 4; ++j) { float x = cu[j] + (pv[j] - cu[j]) * m4[j];
;             if (kind == 0) x = 1.0f - 2.0f * __builtin_amdgcn_rcpf(__expf(2.0f * x) + 1.0f); else if (kind >= 2) x = sigmoid_f(x);
;             v[j] = x; }
;         u32x2 w; w.x = pg8::cvt_pk_bf16(v[0], v[1]); w.y = pg8::cvt_pk_bf16(v[2], v[3]);
;         *(u32x2*)(LA + (size_t)row * 256 + lane * 4) = w;
;         c = nc; p = np;
.Lp5_keep4:
	v_pk_add_f32 v[12:13], v[12:13], v[8:9] neg_lo:[0,1] neg_hi:[0,1]
	v_pk_add_f32 v[14:15], v[14:15], v[10:11] neg_lo:[0,1] neg_hi:[0,1]
	v_pk_fma_f32 v[16:17], v[12:13], v[4:5], v[8:9]
	v_pk_fma_f32 v[18:19], v[14:15], v[6:7], v[10:11]
	v_mul_f32_e32 v20, v3, v16
	v_mul_f32_e32 v21, v3, v17
	v_mul_f32_e32 v22, v3, v18
	v_mul_f32_e32 v23, v3, v19
	v_exp_f32_e32 v20, v20
	v_exp_f32_e32 v21, v21
	v_exp_f32_e32 v22, v22
	v_exp_f32_e32 v23, v23
	v_add_f32_e32 v20, 1.0, v20
	v_add_f32_e32 v21, 1.0, v21
	v_add_f32_e32 v22, 1.0, v22
	v_add_f32_e32 v23, 1.0, v23
	v_rcp_f32_e32 v20, v20
	v_rcp_f32_e32 v21, v21
	v_rcp_f32_e32 v22, v22
	v_rcp_f32_e32 v23, v23
	v_fma_f32 v24, v20, -2.0, 1.0
	v_fma_f32 v25, v21, -2.0, 1.0
	v_fma_f32 v26, v22, -2.0, 1.0
	v_fma_f32 v27, v23, -2.0, 1.0
	v_cndmask_b32_e64 v20, v20, v16, s[24:25]
	v_cndmask_b32_e64 v21, v21, v17, s[24:25]
	v_cndmask_b32_e64 v22, v22, v18, s[24:25]
	v_cndmask_b32_e64 v23, v23, v19, s[24:25]
	v_cndmask_b32_e64 v20, v20, v24, s[22:23]
	v_cndmask_b32_e64 v21, v21, v25, s[22:23]
	v_cndmask_b32_e64 v22, v22, v26, s[22:23]
	v_cndmask_b32_e64 v23, v23, v27, s[22:23]
	v_cvt_pk_bf16_f32 v20, v20, v21
	v_cvt_pk_bf16_f32 v21, v22, v23
	s_add_u32 s20, s20, 0x100000
	s_addc_u32 s21, s21, 0
	global_store_dwordx2 v2, v[20:21], s[20:21]
	s_waitcnt vmcnt(9)
	v_lshlrev_b32_e32 v8, 16, v52
	v_and_b32_e32 v9, 0xffff0000, v52
	v_lshlrev_b32_e32 v10, 16, v53
	v_and_b32_e32 v11, 0xffff0000, v53
	v_lshlrev_b32_e32 v12, 16, v54
	v_and_b32_e32 v13, 0xffff0000, v54
	v_lshlrev_b32_e32 v14, 16, v55
	v_and_b32_e32 v15, 0xffff0000, v55
	s_cmp_lg_u32 s6, 0
	s_cbranch_scc1 .Lp5_keep5
	v_mov_b32_e32 v12, 0
	v_mov_b32_e32 v13, 0
	v_mov_b32_e32 v14, 0
	v_mov_b32_e32 v15, 0
.Lp5_keep5:
	v_pk_add_f32 v[12:13], v[12:13], v[8:9] neg_lo:[0,1] neg_hi:[0,1]
	v_pk_add_f32 v[14:15], v[14:15], v[10:11] neg_lo:[0,1] neg_hi:[0,1]
	v_pk_fma_f32 v[16:17], v[12:13], v[4:5], v[8:9]
	v_pk_fma_f32 v[18:19], v[14:15], v[6:7], v[10:11]
	v_mul_f32_e32 v20, v3, v16
	v_mul_f32_e32 v21, v3, v17
	v_mul_f32_e32 v22, v3, v18
	v_mul_f32_e32 v23, v3, v19
	v_exp_f32_e32 v20, v20
	v_exp_f32_e32 v21, v21
	v_exp_f32_e32 v22, v22
	v_exp_f32_e32 v23, v23
	v_add_f32_e32 v20, 1.0, v20
	v_add_f32_e32 v21, 1.0, v21
	v_add_f32_e32 v22, 1.0, v22
	v_add_f32_e32 v23, 1.0, v23
	v_rcp_f32_e32 v20, v20
	v_rcp_f32_e32 v21, v21
	v_rcp_f32_e32 v22, v22
	v_rcp_f32_e32 v23, v23
	v_fma_f32 v24, v20, -2.0, 1.0
	v_fma_f32 v25, v21, -2.0, 1.0
	v_fma_f32 v26, v22, -2.0, 1.0
	v_fma_f32 v27, v23, -2.0, 1.0
	v_cndmask_b32_e64 v20, v20, v16, s[24:25]
	v_cndmask_b32_e64 v21, v21, v17, s[24:25]
	v_cndmask_b32_e64 v22, v22, v18, s[24:25]
	v_cndmask_b32_e64 v23, v23, v19, s[24:25]
	v_cndmask_b32_e64 v20, v20, v24, s[22:23]
	v_cndmask_b32_e64 v21, v21, v25, s[22:23]
	v_cndmask_b32_e64 v22, v22, v26, s[22:23]
	v_cndmask_b32_e64 v23, v23, v27, s[22:23]
	v_cvt_pk_bf16_f32 v20, v20, v21
	v_cvt_pk_bf16_f32 v21, v22, v23
	s_add_u32 s20, s20, 0x100000
	s_addc_u32 s21, s21, 0
	global_store_dwordx2 v2, v[20:21], s[20:21]
	s_waitcnt vmcnt(8)
	v_lshlrev_b32_e32 v8, 16, v56
	v_and_b32_e32 v9, 0xffff0000, v56
	v_lshlrev_b32_e32 v10, 16, v57
	v_and_b32_e32 v11, 0xffff0000, v57
	v_lshlrev_b32_e32 v12, 16, v58
	v_and_b32_e32 v13, 0xffff0000, v58
	v_lshlrev_b32_e32 v14, 16, v59
	v_and_b32_e32 v15, 0xffff0000, v59
	s_cmp_lg_u32 s6, 0
	s_cbranch_scc1 .Lp5_keep6
	v_mov_b32_e32 v12, 0
	v_mov_b32_e32 v13, 0
	v_mov_b32_e32 v14, 0
	v_mov_b32_e32 v15, 0
; __device__ __forceinline__ unsigned cvt_pk_bf16(float lo, float hi) { const f32x2_t v = {lo, hi}; const bf16x2_t b = __builtin_convertvector(v, bf16x2_t); return __builtin_bit_cast(unsigned, b); }
; __device__ __forceinline__ float lo_bf(unsigned x) { return __uint_as_float(x << 16); }
; __device__ __forceinline__ float hi_bf(unsigned x) { return __uint_as_float(x & 0xffff0000u); }
; __device__ __forceinline__ float sigmoid_f(float x) { return __builtin_amdgcn_rcpf(1.0f + __expf(-x)); }
; __device__ __forceinline__ void lora_prep(PR P, const int wv) {
;     ...
;     for (int row = gw; row < MT; row += nw) {
;         const int nrow = row + nw < MT ? row + nw : last; const int npr = prev_row(nrow);
;         nc = *(const u32x2*)(PS + (size_t)nrow * NCOLS + 1536 + lane * 4); np = *(const u32x2*)(PS + (size_t)(npr >= 0 ? npr : nrow) * NCOLS + 1536 + lane * 4);
;         if (prev_row(row) < 0) p = (u32x2){0u, 0u};
;         float v[4]; const float cu[4] = {lo_bf(c.x), hi_bf(c.x), lo_bf(c.y), hi_bf(c.y)}, pv[4] = {lo_bf(p.x), hi_bf(p.x), lo_bf(p.y), hi_bf(p.y)}, m4[4] = {mu.x, mu.y, mu.z, mu.w};
; #pragma unroll
;         for (int j = 0; j < 4; ++j) { float x = cu[j] + (pv[j] - cu[j]) * m4[j];
;             if (kind == 0) x = 1.0f - 2.0f * __builtin_amdgcn_rcpf(__expf(2.0f * x) + 1.0f); else if (kind >= 2) x = sigmoid_f(x);
;             v[j] = x; }
;         u32x2 w; w.x = pg8::cvt_pk_bf16(v[0], v[1]); w.y = pg8::cvt_pk_bf16(v[2], v[3]);
;         *(u32x2*)(LA + (size_t)row * 256 + lane * 4) = w;
;         c = nc; p = np;
.Lp5_keep6:
	v_pk_add_f32 v[12:13], v[12:13], v[8:9] neg_lo:[0,1] neg_hi:[0,1]
	v_pk_add_f32 v[14:15], v[14:15], v[10:11] neg_lo:[0,1] neg_hi:[0,1]
	v_pk_fma_f32 v[16:17], v[12:13], v[4:5], v[8:9]
	v_pk_fma_f32 v[18:19], v[14:15], v[6:7], v[10:11]
	v_mul_f32_e32 v20, v3, v16
	v_mul_f32_e32 v21, v3, v17
	v_mul_f32_e32 v22, v3, v18
	v_mul_f32_e32 v23, v3, v19
	v_exp_f32_e32 v20, v20
	v_exp_f32_e32 v21, v21
	v_exp_f32_e32 v22, v22
	v_exp_f32_e32 v23, v23
	v_add_f32_e32 v20, 1.0, v20
	v_add_f32_e32 v21, 1.0, v21
	v_add_f32_e32 v22, 1.0, v22
	v_add_f32_e32 v23, 1.0, v23
	v_rcp_f32_e32 v20, v20
	v_rcp_f32_e32 v21, v21
	v_rcp_f32_e32 v22, v22
	v_rcp_f32_e32 v23, v23
	v_fma_f32 v24, v20, -2.0, 1.0
	v_fma_f32 v25, v21, -2.0, 1.0
	v_fma_f32 v26, v22, -2.0, 1.0
	v_fma_f32 v27, v23, -2.0, 1.0
	v_cndmask_b32_e64 v20, v20, v16, s[24:25]
	v_cndmask_b32_e64 v21, v21, v17, s[24:25]
	v_cndmask_b32_e64 v22, v22, v18, s[24:25]
	v_cndmask_b32_e64 v23, v23, v19, s[24:25]
	v_cndmask_b32_e64 v20, v20, v24, s[22:23]
	v_cndmask_b32_e64 v21, v21, v25, s[22:23]
	v_cndmask_b32_e64 v22, v22, v26, s[22:23]
	v_cndmask_b32_e64 v23, v23, v27, s[22:23]
	v_cvt_pk_bf16_f32 v20, v20, v21
	v_cvt_pk_bf16_f32 v21, v22, v23
	s_add_u32 s20, s20, 0x100000
	s_addc_u32 s21, s21, 0
	global_store_dwordx2 v2, v[20:21], s[20:21]
	s_waitcnt vmcnt(7)
	v_lshlrev_b32_e32 v8, 16, v60
	v_and_b32_e32 v9, 0xffff0000, v60
	v_lshlrev_b32_e32 v10, 16, v61
	v_and_b32_e32 v11, 0xffff0000, v61
	v_lshlrev_b32_e32 v12, 16, v62
	v_and_b32_e32 v13, 0xffff0000, v62
	v_lshlrev_b32_e32 v14, 16, v63
	v_and_b32_e32 v15, 0xffff0000, v63
	s_cmp_lg_u32 s6, 0
	s_cbranch_scc1 .Lp5_keep7
	v_mov_b32_e32 v12, 0
	v_mov_b32_e32 v13, 0
	v_mov_b32_e32 v14, 0
	v_mov_b32_e32 v15, 0
.Lp5_keep7:
	v_pk_add_f32 v[12:13], v[12:13], v[8:9] neg_lo:[0,1] neg_hi:[0,1]
	v_pk_add_f32 v[14:15], v[14:15], v[10:11] neg_lo:[0,1] neg_hi:[0,1]
	v_pk_fma_f32 v[16:17], v[12:13], v[4:5], v[8:9]
	v_pk_fma_f32 v[18:19], v[14:15], v[6:7], v[10:11]
	v_mul_f32_e32 v20, v3, v16
	v_mul_f32_e32 v21, v3, v17
	v_mul_f32_e32 v22, v3, v18
	v_mul_f32_e32 v23, v3, v19
	v_exp_f32_e32 v20, v20
	v_exp_f32_e32 v21, v21
	v_exp_f32_e32 v22, v22
	v_exp_f32_e32 v23, v23
	v_add_f32_e32 v20, 1.0, v20
	v_add_f32_e32 v21, 1.0, v21
	v_add_f32_e32 v22, 1.0, v22
	v_add_f32_e32 v23, 1.0, v23
	v_rcp_f32_e32 v20, v20
	v_rcp_f32_e32 v21, v21
	v_rcp_f32_e32 v22, v22
	v_rcp_f32_e32 v23, v23
	v_fma_f32 v24, v20, -2.0, 1.0
	v_fma_f32 v25, v21, -2.0, 1.0
	v_fma_f32 v26, v22, -2.0, 1.0
	v_fma_f32 v27, v23, -2.0, 1.0
	v_cndmask_b32_e64 v20, v20, v16, s[24:25]
	v_cndmask_b32_e64 v21, v21, v17, s[24:25]
	v_cndmask_b32_e64 v22, v22, v18, s[24:25]
	v_cndmask_b32_e64 v23, v23, v19, s[24:25]
	v_cndmask_b32_e64 v20, v20, v24, s[22:23]
	v_cndmask_b32_e64 v21, v21, v25, s[22:23]
	v_cndmask_b32_e64 v22, v22, v26, s[22:23]
	v_cndmask_b32_e64 v23, v23, v27, s[22:23]
	v_cvt_pk_bf16_f32 v20, v20, v21
	v_cvt_pk_bf16_f32 v21, v22, v23
	s_add_u32 s20, s20, 0x100000
	s_addc_u32 s21, s21, 0
	global_store_dwordx2 v2, v[20:21], s[20:21]
	s_cmp_lt_u32 s6, 0x200
	s_cbranch_scc0 .Lp5_done
	s_waitcnt vmcnt(8)
	v_lshlrev_b32_e32 v8, 16, v64
	v_and_b32_e32 v9, 0xffff0000, v64
	v_lshlrev_b32_e32 v10, 16, v65
	v_and_b32_e32 v11, 0xffff0000, v65
	v_lshlrev_b32_e32 v12, 16, v66
	v_and_b32_e32 v13, 0xffff0000, v66
	v_lshlrev_b32_e32 v14, 16, v67
	v_and_b32_e32 v15, 0xffff0000, v67
	v_pk_add_f32 v[12:13], v[12:13], v[8:9] neg_lo:[0,1] neg_hi:[0,1]
	v_pk_add_f32 v[14:15], v[14:15], v[10:11] neg_lo:[0,1] neg_hi:[0,1]
	v_pk_fma_f32 v[16:17], v[12:13], v[4:5], v[8:9]
	v_pk_fma_f32 v[18:19], v[14:15], v[6:7], v[10:11]
	v_mul_f32_e32 v20, v3, v16
	v_mul_f32_e32 v21, v3, v17
	v_mul_f32_e32 v22, v3, v18
	v_mul_f32_e32 v23, v3, v19
	v_exp_f32_e32 v20, v20
	v_exp_f32_e32 v21, v21
	v_exp_f32_e32 v22, v22
	v_exp_f32_e32 v23, v23
	v_add_f32_e32 v20, 1.0, v20
	v_add_f32_e32 v21, 1.0, v21
	v_add_f32_e32 v22, 1.0, v22
	v_add_f32_e32 v23, 1.0, v23
	v_rcp_f32_e32 v20, v20
	v_rcp_f32_e32 v21, v21
	v_rcp_f32_e32 v22, v22
	v_rcp_f32_e32 v23, v23
	v_fma_f32 v24, v20, -2.0, 1.0
	v_fma_f32 v25, v21, -2.0, 1.0
	v_fma_f32 v26, v22, -2.0, 1.0
	v_fma_f32 v27, v23, -2.0, 1.0
	v_cndmask_b32_e64 v20, v20, v16, s[24:25]
	v_cndmask_b32_e64 v21, v21, v17, s[24:25]
	v_cndmask_b32_e64 v22, v22, v18, s[24:25]
	v_cndmask_b32_e64 v23, v23, v19, s[24:25]
	v_cndmask_b32_e64 v20, v20, v24, s[22:23]
	v_cndmask_b32_e64 v21, v21, v25, s[22:23]
	v_cndmask_b32_e64 v22, v22, v26, s[22:23]
	v_cndmask_b32_e64 v23, v23, v27, s[22:23]
	v_cvt_pk_bf16_f32 v20, v20, v21
	v_cvt_pk_bf16_f32 v21, v22, v23
	s_add_u32 s20, s20, 0x100000
	s_addc_u32 s21, s21, 0
	global_store_dwordx2 v2, v[20:21], s[20:21]
.Lp5_done:
	s_mov_b32 s49, 0
